# v31 + static s_setprio 1 for waves 4-7 (tid>=256) for the whole kernel
# baseline (speedup 1.0000x reference)
; #define LAS __attribute__((address_space(3)))
; __global__ void __launch_bounds__(512, 2) mega_fwd(Params P) {
;   __shared__ __attribute__((aligned(16))) unsigned char smem[LDS_BYTES];
;   __shared__ uint4 xb_words;
;   cg::grid_group grid = cg::this_grid();
;   if (P.ws == nullptr) grid.sync();
;   if (threadIdx.x == 0) xb_words = make_uint4(0u, 0u, 0u, 0u);
;   __syncthreads();
;   XcdBarrier xbar = xcd_barrier_post((unsigned*)(P.ws + OFF_BAR), (volatile LAS unsigned*)&xb_words);
_Z8mega_fwd6Params:
	s_load_dwordx4 s[72:75], s[0:1], 0xc0
	s_add_u32 s4, s0, 0xc8
	s_addc_u32 s5, s1, 0
	s_mov_b32 s70, s2
	v_readfirstlane_b32 s100, v0
	s_and_b32 s100, s100, 0x3ff
	s_cmp_lt_u32 s100, 0x100
	s_cbranch_scc1 .Lmy_prio_skip
	s_setprio 1
.Lmy_prio_skip:
	s_mov_b64 s[2:3], 0
	s_waitcnt lgkmcnt(0)
	s_cmp_eq_u64 s[72:73], 0
	s_cbranch_scc1 .LBB0_2
	v_and_b32_e32 v192, 0x3ff, v0
	s_branch .LBB0_3
